# v22 + scan-final initial-state loop software-pipelined: 14 loads (7 rounds of decay+U tiles) in flight through free registers, counted vmcnt, same arithmetic order; odd remainder batched
# baseline (speedup 1.0000x reference)
; template <bool FINAL>
; LPHASE void phase_gla_scan(char* ws_, int nseq_, char* ldsg, LAS unsigned char* lds) {
;     ...
;     if (FINAL) {
;       const int np = dir ? (nls - 1 - ls) : ls;
;       f32x4 W[8];
; #pragma unroll
;       for (int t = 0; t < 8; ++t) W[t] = (f32x4){1.f, 1.f, 1.f, 1.f};
; #pragma unroll 2
;       for (int q = 0; q < np; ++q) { const int ps = dir ? (ls + 1 + q) : (ls - 1 - q); const int psg = s * nls + ps;
;         const f32x4* U = (const f32x4*)(Ub + (((size_t)psg * 4 + hd) * 2 + dir) * 128 * 256) + ((size_t)(colb >> 4) * 8) * 64 + lane; const float* D = Db + (((size_t)psg * 4 + hd) * 2 + dir) * 128;
; #pragma unroll
;         for (int t = 0; t < 8; ++t) { const f32x4 dv = *(const f32x4*)(D + 16 * t + 4 * fq); const f32x4 uv = U[t * 64];
;           S[t] += W[t] * uv; W[t] *= dv; } }
;     }
.LBB0_365:
	s_not_b32 s90, s41
	s_add_i32 s67, s38, s41
	s_add_i32 s94, s76, s90
	s_and_b64 s[90:91], s[62:63], exec
	s_cselect_b32 s90, s94, s67
	s_add_i32 s90, s90, s3
	s_ashr_i32 s91, s90, 31
	s_lshl_b64 s[90:91], s[90:91], 3
	s_or_b64 s[90:91], s[90:91], s[28:29]
	s_lshl_b64 vcc, s[90:91], 17
	s_lshl_b64 s[90:91], s[90:91], 9
	v_lshl_add_u64 v[94:95], v[116:117], 0, s[90:91]
	v_lshl_add_u64 v[92:93], v[10:11], 0, vcc
	s_xor_b32 s90, s41, -2
	s_add_i32 s67, s67, 1
	s_add_i32 s94, s76, s90
	s_and_b64 s[90:91], s[62:63], exec
	s_cselect_b32 s67, s94, s67
	s_add_i32 s90, s67, s3
	s_ashr_i32 s91, s90, 31
	s_lshl_b64 s[90:91], s[90:91], 3
	s_or_b64 s[90:91], s[90:91], s[28:29]
	s_add_i32 s41, s41, 2
	s_lshl_b64 vcc, s[90:91], 17
	s_lshl_b64 s[90:91], s[90:91], 9
	v_lshl_add_u64 v[122:123], v[116:117], 0, s[90:91]
	v_lshl_add_u64 v[124:125], v[10:11], 0, vcc
	v_add_co_u32_e32 v96, vcc, s4, v92
	s_nop 1
	v_addc_co_u32_e32 v97, vcc, 0, v93, vcc
	v_add_co_u32_e32 v126, vcc, s4, v124
	s_nop 1
	v_addc_co_u32_e32 v127, vcc, 0, v125, vcc
	s_cmp_eq_u32 s41, s39
	global_load_dwordx4 v[84:87], v[94:95], off
	global_load_dwordx4 v[88:91], v[92:93], off
	global_load_dwordx4 v[182:185], v[94:95], off offset:64
	global_load_dwordx4 v[186:189], v[92:93], off offset:1024
	global_load_dwordx4 v[190:193], v[94:95], off offset:128
	global_load_dwordx4 v[194:197], v[92:93], off offset:2048
	global_load_dwordx4 v[198:201], v[94:95], off offset:192
	global_load_dwordx4 v[202:205], v[92:93], off offset:3072
	global_load_dwordx4 v[206:209], v[94:95], off offset:256
	global_load_dwordx4 v[210:213], v[96:97], off
	global_load_dwordx4 v[214:217], v[94:95], off offset:320
	global_load_dwordx4 v[218:221], v[96:97], off offset:1024
	global_load_dwordx4 v[222:225], v[94:95], off offset:384
	global_load_dwordx4 v[244:247], v[96:97], off offset:2048
	s_waitcnt vmcnt(12)
	v_pk_fma_f32 v[64:65], v[26:27], v[90:91], v[64:65]
	v_pk_fma_f32 v[68:69], v[24:25], v[88:89], v[68:69]
	v_pk_mul_f32 v[26:27], v[26:27], v[86:87]
	v_pk_mul_f32 v[24:25], v[24:25], v[84:85]
	global_load_dwordx4 v[84:87], v[94:95], off offset:448
	global_load_dwordx4 v[88:91], v[96:97], off offset:3072
	s_waitcnt vmcnt(12)
	v_pk_fma_f32 v[66:67], v[30:31], v[188:189], v[66:67]
	v_pk_fma_f32 v[70:71], v[28:29], v[186:187], v[70:71]
	v_pk_mul_f32 v[30:31], v[30:31], v[184:185]
	v_pk_mul_f32 v[28:29], v[28:29], v[182:183]
	global_load_dwordx4 v[182:185], v[122:123], off
	global_load_dwordx4 v[186:189], v[124:125], off
	s_waitcnt vmcnt(12)
	v_pk_fma_f32 v[60:61], v[34:35], v[196:197], v[60:61]
	v_pk_fma_f32 v[62:63], v[32:33], v[194:195], v[62:63]
	v_pk_mul_f32 v[34:35], v[34:35], v[192:193]
	v_pk_mul_f32 v[32:33], v[32:33], v[190:191]
	global_load_dwordx4 v[190:193], v[122:123], off offset:64
	global_load_dwordx4 v[194:197], v[124:125], off offset:1024
	s_waitcnt vmcnt(12)
	v_pk_fma_f32 v[56:57], v[74:75], v[204:205], v[56:57]
	v_pk_fma_f32 v[58:59], v[72:73], v[202:203], v[58:59]
	v_pk_mul_f32 v[74:75], v[74:75], v[200:201]
	v_pk_mul_f32 v[72:73], v[72:73], v[198:199]
	global_load_dwordx4 v[198:201], v[122:123], off offset:128
	global_load_dwordx4 v[202:205], v[124:125], off offset:2048
	s_waitcnt vmcnt(12)
	v_pk_fma_f32 v[40:41], v[38:39], v[212:213], v[40:41]
	v_pk_fma_f32 v[42:43], v[36:37], v[210:211], v[42:43]
	v_pk_mul_f32 v[38:39], v[38:39], v[208:209]
	v_pk_mul_f32 v[36:37], v[36:37], v[206:207]
	global_load_dwordx4 v[206:209], v[122:123], off offset:192
	global_load_dwordx4 v[210:213], v[124:125], off offset:3072
	s_waitcnt vmcnt(12)
	v_pk_fma_f32 v[44:45], v[78:79], v[220:221], v[44:45]
	v_pk_fma_f32 v[46:47], v[76:77], v[218:219], v[46:47]
	v_pk_mul_f32 v[78:79], v[78:79], v[216:217]
	v_pk_mul_f32 v[76:77], v[76:77], v[214:215]
	global_load_dwordx4 v[214:217], v[122:123], off offset:256
	global_load_dwordx4 v[218:221], v[126:127], off
	s_waitcnt vmcnt(12)
	v_pk_fma_f32 v[48:49], v[82:83], v[246:247], v[48:49]
	v_pk_fma_f32 v[50:51], v[80:81], v[244:245], v[50:51]
	v_pk_mul_f32 v[82:83], v[82:83], v[224:225]
	v_pk_mul_f32 v[80:81], v[80:81], v[222:223]
	global_load_dwordx4 v[222:225], v[122:123], off offset:320
	global_load_dwordx4 v[244:247], v[126:127], off offset:1024
	s_waitcnt vmcnt(12)
	v_pk_fma_f32 v[54:55], v[14:15], v[90:91], v[54:55]
	v_pk_fma_f32 v[52:53], v[12:13], v[88:89], v[52:53]
	v_pk_mul_f32 v[14:15], v[14:15], v[86:87]
	v_pk_mul_f32 v[12:13], v[12:13], v[84:85]
	global_load_dwordx4 v[84:87], v[122:123], off offset:384
	global_load_dwordx4 v[88:91], v[126:127], off offset:2048
	s_waitcnt vmcnt(12)
	v_pk_fma_f32 v[64:65], v[26:27], v[188:189], v[64:65]
	v_pk_fma_f32 v[68:69], v[24:25], v[186:187], v[68:69]
	v_pk_mul_f32 v[26:27], v[26:27], v[184:185]
	v_pk_mul_f32 v[24:25], v[24:25], v[182:183]
	global_load_dwordx4 v[182:185], v[122:123], off offset:448
	global_load_dwordx4 v[186:189], v[126:127], off offset:3072
	s_waitcnt vmcnt(12)
	v_pk_fma_f32 v[66:67], v[30:31], v[196:197], v[66:67]
	v_pk_fma_f32 v[70:71], v[28:29], v[194:195], v[70:71]
	v_pk_mul_f32 v[30:31], v[30:31], v[192:193]
	v_pk_mul_f32 v[28:29], v[28:29], v[190:191]
	s_waitcnt vmcnt(10)
	v_pk_fma_f32 v[60:61], v[34:35], v[204:205], v[60:61]
	v_pk_fma_f32 v[62:63], v[32:33], v[202:203], v[62:63]
	v_pk_mul_f32 v[34:35], v[34:35], v[200:201]
	v_pk_mul_f32 v[32:33], v[32:33], v[198:199]
	s_waitcnt vmcnt(8)
	v_pk_fma_f32 v[56:57], v[74:75], v[212:213], v[56:57]
	v_pk_fma_f32 v[58:59], v[72:73], v[210:211], v[58:59]
	v_pk_mul_f32 v[74:75], v[74:75], v[208:209]
	v_pk_mul_f32 v[72:73], v[72:73], v[206:207]
	s_waitcnt vmcnt(6)
	v_pk_fma_f32 v[40:41], v[38:39], v[220:221], v[40:41]
	v_pk_fma_f32 v[42:43], v[36:37], v[218:219], v[42:43]
	v_pk_mul_f32 v[38:39], v[38:39], v[216:217]
	v_pk_mul_f32 v[36:37], v[36:37], v[214:215]
	s_waitcnt vmcnt(4)
	v_pk_fma_f32 v[44:45], v[78:79], v[246:247], v[44:45]
	v_pk_fma_f32 v[46:47], v[76:77], v[244:245], v[46:47]
	v_pk_mul_f32 v[78:79], v[78:79], v[224:225]
	v_pk_mul_f32 v[76:77], v[76:77], v[222:223]
	s_waitcnt vmcnt(2)
	v_pk_fma_f32 v[48:49], v[82:83], v[90:91], v[48:49]
	v_pk_fma_f32 v[50:51], v[80:81], v[88:89], v[50:51]
	v_pk_mul_f32 v[82:83], v[82:83], v[86:87]
	v_pk_mul_f32 v[80:81], v[80:81], v[84:85]
	s_waitcnt vmcnt(0)
	v_pk_fma_f32 v[54:55], v[14:15], v[188:189], v[54:55]
	v_pk_fma_f32 v[52:53], v[12:13], v[186:187], v[52:53]
	v_pk_mul_f32 v[14:15], v[14:15], v[184:185]
	v_pk_mul_f32 v[12:13], v[12:13], v[182:183]
	s_cbranch_scc0 .LBB0_365
	s_mov_b32 s94, s97
	s_bitcmp0_b32 s40, 0
	s_cbranch_scc0 .LBB0_369
	s_branch .LBB0_370

; template <bool FINAL>
; LPHASE void phase_gla_scan(char* ws_, int nseq_, char* ldsg, LAS unsigned char* lds) {
;     ...
; #pragma unroll 2
;       for (int q = 0; q < np; ++q) { const int ps = dir ? (ls + 1 + q) : (ls - 1 - q); const int psg = s * nls + ps;
;         const f32x4* U = (const f32x4*)(Ub + (((size_t)psg * 4 + hd) * 2 + dir) * 128 * 256) + ((size_t)(colb >> 4) * 8) * 64 + lane; const float* D = Db + (((size_t)psg * 4 + hd) * 2 + dir) * 128;
; #pragma unroll
;         for (int t = 0; t < 8; ++t) { const f32x4 dv = *(const f32x4*)(D + 16 * t + 4 * fq); const f32x4 uv = U[t * 64];
;           S[t] += W[t] * uv; W[t] *= dv; } }
.LBB0_369:
	s_not_b32 s28, s39
	s_add_i32 s38, s38, s39
	s_add_i32 s39, s76, s28
	s_and_b64 s[28:29], s[62:63], exec
	s_cselect_b32 s28, s39, s38
	s_add_i32 s28, s28, s3
	s_ashr_i32 s29, s28, 31
	s_lshl_b64 s[28:29], s[28:29], 3
	s_or_b64 s[26:27], s[26:27], s[28:29]
	s_or_b64 s[26:27], s[26:27], s[42:43]
	s_lshl_b64 s[26:27], s[26:27], 17
	v_lshl_add_u64 v[10:11], v[10:11], 0, s[26:27]
	v_add_co_u32_e32 v96, vcc, s4, v10
	s_nop 1
	v_addc_co_u32_e32 v97, vcc, 0, v11, vcc
	global_load_dwordx4 v[84:87], v[10:11], off
	global_load_dwordx4 v[88:91], v[10:11], off offset:1024
	global_load_dwordx4 v[182:185], v[10:11], off offset:2048
	global_load_dwordx4 v[186:189], v[10:11], off offset:3072
	global_load_dwordx4 v[190:193], v[96:97], off
	global_load_dwordx4 v[194:197], v[96:97], off offset:1024
	global_load_dwordx4 v[198:201], v[96:97], off offset:2048
	global_load_dwordx4 v[202:205], v[96:97], off offset:3072
	s_waitcnt vmcnt(7)
	v_pk_fma_f32 v[64:65], v[26:27], v[86:87], v[64:65]
	v_pk_fma_f32 v[68:69], v[24:25], v[84:85], v[68:69]
	s_waitcnt vmcnt(6)
	v_pk_fma_f32 v[66:67], v[30:31], v[90:91], v[66:67]
	v_pk_fma_f32 v[70:71], v[28:29], v[88:89], v[70:71]
	s_waitcnt vmcnt(5)
	v_pk_fma_f32 v[60:61], v[34:35], v[184:185], v[60:61]
	v_pk_fma_f32 v[62:63], v[32:33], v[182:183], v[62:63]
	s_waitcnt vmcnt(4)
	v_pk_fma_f32 v[56:57], v[74:75], v[188:189], v[56:57]
	v_pk_fma_f32 v[58:59], v[72:73], v[186:187], v[58:59]
	s_waitcnt vmcnt(3)
	v_pk_fma_f32 v[40:41], v[38:39], v[192:193], v[40:41]
	v_pk_fma_f32 v[42:43], v[36:37], v[190:191], v[42:43]
	s_waitcnt vmcnt(2)
	v_pk_fma_f32 v[44:45], v[78:79], v[196:197], v[44:45]
	v_pk_fma_f32 v[46:47], v[76:77], v[194:195], v[46:47]
	s_waitcnt vmcnt(1)
	v_pk_fma_f32 v[48:49], v[82:83], v[200:201], v[48:49]
	v_pk_fma_f32 v[50:51], v[80:81], v[198:199], v[50:51]
	s_waitcnt vmcnt(0)
	v_pk_fma_f32 v[54:55], v[14:15], v[204:205], v[54:55]
	v_pk_fma_f32 v[52:53], v[12:13], v[202:203], v[52:53]
	v_mov_b32_e32 v10, v96
	v_mov_b32_e32 v11, v97
